# in-proj strip A loads in one burst; prologue x-copy rows in one burst; weight-transpose loop keeps next item's 32 loads in flight (gain loads issued first, counted waits)
# speedup vs baseline: 1.0007x; 1.0007x over previous
; __device__ __forceinline__ void inproj_strip(const bf16_t* __restrict__ xb, const bf16_t* __restrict__ wt, const u64_t* ss, bf16_t* proj, int G, int bx, LAS unsigned char* lds) {
;     ...
;     for (int rb = bx; rb < M / 32; rb += G) {
;         const bf16_t* ap = xb + (size_t)(rb * 32 + r32) * D + wid * 256 + hi * 8;
;         const bf16_t* bp = wt + (size_t)(GAF + r32) * D + wid * 256 + hi * 8;
;         f32x16 acc = f32x16{};
; #pragma unroll
;         for (int ks = 0; ks < 16; ++ks) { const bf16x8 av = *(const bf16x8*)(ap + ks * 16), bv = *(const bf16x8*)(bp + ks * 16);
;             acc = __builtin_amdgcn_mfma_f32_32x32x16_bf16(av, bv, acc, 0, 0, 0); }
;         __syncthreads();
; #pragma unroll
;         for (int r = 0; r < 16; ++r) red[(wid * 32 + ((r & 3) + 8 * (r >> 2) + 4 * hi)) * 33 + r32] = acc[r];
;         __syncthreads();
.LBB0_229:
	s_lshl_b32 s7, s6, 5
	v_or_b32_e32 v2, s7, v82
	v_ashrrev_i32_e32 v3, 31, v2
	v_lshlrev_b64 v[2:3], 12, v[2:3]
	v_lshl_add_u64 v[92:93], v[84:85], 0, v[2:3]
	flat_load_dwordx4 v[2:5], v[92:93]
	flat_load_dwordx4 v[88:91], v[92:93] offset:32
	flat_load_dwordx4 v[100:103], v[92:93] offset:64
	flat_load_dwordx4 v[104:107], v[92:93] offset:96
	flat_load_dwordx4 v[108:111], v[92:93] offset:128
	flat_load_dwordx4 v[112:115], v[92:93] offset:160
	flat_load_dwordx4 v[116:119], v[92:93] offset:192
	flat_load_dwordx4 v[120:123], v[92:93] offset:224
	flat_load_dwordx4 v[124:127], v[92:93] offset:256
	flat_load_dwordx4 v[128:131], v[92:93] offset:288
	flat_load_dwordx4 v[132:135], v[92:93] offset:320
	flat_load_dwordx4 v[136:139], v[92:93] offset:352
	flat_load_dwordx4 v[140:143], v[92:93] offset:384
	flat_load_dwordx4 v[144:147], v[92:93] offset:416
	flat_load_dwordx4 v[148:151], v[92:93] offset:448
	flat_load_dwordx4 v[152:155], v[92:93] offset:480
	v_add_u32_e32 v94, 0xc00, v87
	s_waitcnt vmcnt(0) lgkmcnt(0)
	v_mfma_f32_32x32x16_bf16 v[2:17], v[2:5], v[30:33], 0
	v_mfma_f32_32x32x16_bf16 v[2:17], v[88:91], v[34:37], v[2:17]
	v_mfma_f32_32x32x16_bf16 v[2:17], v[100:103], v[38:41], v[2:17]
	v_mfma_f32_32x32x16_bf16 v[2:17], v[104:107], v[42:45], v[2:17]
	v_mfma_f32_32x32x16_bf16 v[2:17], v[108:111], v[46:49], v[2:17]
	v_mfma_f32_32x32x16_bf16 v[2:17], v[112:115], v[50:53], v[2:17]
	v_mfma_f32_32x32x16_bf16 v[2:17], v[116:119], v[54:57], v[2:17]
	v_mfma_f32_32x32x16_bf16 v[2:17], v[120:123], v[58:61], v[2:17]
	v_mfma_f32_32x32x16_bf16 v[2:17], v[124:127], v[62:65], v[2:17]
	v_mfma_f32_32x32x16_bf16 v[2:17], v[128:131], v[66:69], v[2:17]
	v_mfma_f32_32x32x16_bf16 v[2:17], v[132:135], v[70:73], v[2:17]
	v_mfma_f32_32x32x16_bf16 v[2:17], v[136:139], v[74:77], v[2:17]
	v_mfma_f32_32x32x16_bf16 v[2:17], v[140:143], v[78:81], v[2:17]
	v_mfma_f32_32x32x16_bf16 v[2:17], v[144:147], v[18:21], v[2:17]
	v_mfma_f32_32x32x16_bf16 v[2:17], v[148:151], v[22:25], v[2:17]
	v_add_u32_e32 v92, 0x400, v87
	v_add_u32_e32 v93, 0x800, v87
	s_waitcnt lgkmcnt(0)
	s_barrier
	s_waitcnt vmcnt(0)
	v_mfma_f32_32x32x16_bf16 v[2:17], v[152:155], v[26:29], v[2:17]
	s_nop 11
	ds_write2_b32 v87, v2, v3 offset1:33
	ds_write2_b32 v87, v4, v5 offset0:66 offset1:99
	ds_write2_b32 v92, v6, v7 offset0:8 offset1:41
	ds_write2_b32 v92, v8, v9 offset0:74 offset1:107
	ds_write2_b32 v93, v10, v11 offset0:16 offset1:49
	ds_write2_b32 v93, v12, v13 offset0:82 offset1:115
	ds_write2_b32 v94, v14, v15 offset0:24 offset1:57
	ds_write2_b32 v94, v16, v17 offset0:90 offset1:123
	s_waitcnt lgkmcnt(0)
	s_barrier
	s_and_saveexec_b64 s[2:3], s[0:1]
	s_cbranch_execz .LBB0_228
	s_mov_b64 s[4:5], 0
	v_mov_b32_e32 v2, v83

; __device__ __forceinline__ TItem titem_decode(const Args& a, int it) {
;     constexpr int I_IN = (D / 64) * (INW / 32), I_O = (D / 64) * (D / 32), I_UP = (D / 64) * (UPW / 32), I_DN = (DFF / 64) * (D / 32), I_L = I_IN + I_O + I_UP + I_DN;
;     const int L = it / I_L; int r = it % I_L; unsigned char* wl = a.ws + WS_W + (size_t)L * W_LAYER; TItem t;
;     if (r < I_IN) { const int nblk = INW / 32, kb = r / nblk, n0 = (r % nblk) * 32, k0 = kb * 64;
;         t.cs = ((n0 >= GQ && n0 < GK) || (n0 >= SRC_RK && n0 < SRC_RV)) ? 0.125f : 1.f; t.N = INW; t.K = D; t.src = a.w_in + (size_t)L * D * INW + (size_t)k0 * INW + n0; t.gk = a.ln1_g + L * D + k0;
;         const int dn = n0 < SRC_GA ? n0 : (n0 < SRC_GA + 32 ? GAF + (n0 - SRC_GA) : n0 - 32);
;         t.dst = (bf16_t*)(wl + W_IN) + (size_t)dn * D + k0; return t; }
;     r -= I_IN;
;     if (r < I_O) { const int nblk = D / 32, kb = r / nblk, n0 = (r % nblk) * 32, k0 = kb * 64;
;         t.cs = 1.f; t.N = D; t.K = D; t.src = a.w_o + (size_t)L * D * D + (size_t)k0 * D + n0; t.gk = nullptr; t.dst = (bf16_t*)(wl + W_O) + (size_t)n0 * D + k0; return t; }
;     r -= I_O;
;     if (r < I_UP) { const int nblk = UPW / 32, kb = r / nblk, n0 = (r % nblk) * 32, k0 = kb * 64;
;         const int c = n0 < DFF ? n0 : n0 - DFF; const int dst = (c >> 7) * 256 + (c & 127) + (n0 < DFF ? 0 : 128);
;         t.cs = 1.f; t.N = UPW; t.K = D; t.src = a.w_up + (size_t)L * D * UPW + (size_t)k0 * UPW + n0; t.gk = a.ln2_g + L * D + k0; t.dst = (bf16_t*)(wl + W_UP) + (size_t)dst * D + k0; return t; }
;     r -= I_UP;
;     { const int nblk = D / 32, kb = r / nblk, n0 = (r % nblk) * 32, k0 = kb * 64;
;         t.cs = 1.f; t.N = D; t.K = DFF; t.src = a.w_down + (size_t)L * DFF * D + (size_t)k0 * D + n0; t.gk = nullptr; t.dst = (bf16_t*)(wl + W_DN) + (size_t)n0 * DFF + k0; return t; }
; }
; __device__ __forceinline__ void phase_prologue(const Args& a, LAS unsigned char* lds) {
;     ...
;         for (int it = gw; it < I_ALL; it += 2 * NGW) {
;             const bool hasB = it + NGW < I_ALL;
;             if (hasB) { tb = titem_decode(a, it + NGW); TI_LOAD(rb, gb, tb); }
.LBB0_270:
	s_mov_b32 s100, 0
	s_mov_b32 s101, 0
	v_add_u32_e32 v0, s58, v50
	s_mov_b32 s0, 0x18880
	v_cmp_gt_i32_e32 vcc, s0, v0
	s_and_saveexec_b64 s[6:7], vcc
	s_cbranch_execz .LBB0_288
	s_mov_b32 s0, 0xa6f87fd7
	v_mul_hi_i32 v21, v0, s0
	v_add_u32_e32 v21, v21, v0
	v_lshrrev_b32_e32 v22, 31, v21
	v_ashrrev_i32_e32 v21, 14, v21
	v_add_u32_e32 v36, v21, v22
	v_mov_b64_e32 v[22:23], s[56:57]
	v_mul_i32_i24_e32 v21, 0x6220, v36
	v_mad_i64_i32 v[32:33], s[0:1], v36, s77, v[22:23]
	v_sub_u32_e32 v0, v0, v21
	s_movk_i32 s0, 0x181f
	v_ashrrev_i32_e32 v37, 31, v36
	v_cmp_lt_i32_e64 s[0:1], s0, v0
	s_and_saveexec_b64 s[8:9], s[0:1]
	s_xor_b64 s[8:9], exec, s[8:9]
	s_cbranch_execz .LBB0_281
	s_movk_i32 s0, 0x201f
	v_cmp_lt_u32_e64 s[0:1], s0, v0
	s_and_saveexec_b64 s[10:11], s[0:1]
	s_xor_b64 s[10:11], exec, s[10:11]
	s_cbranch_execz .LBB0_278
	s_movk_i32 s0, 0x4c1f
	v_cmp_lt_u32_e64 s[0:1], s0, v0
	s_and_saveexec_b64 s[12:13], s[0:1]
	s_xor_b64 s[0:1], exec, s[12:13]
	s_cbranch_execz .LBB0_275
	v_readlane_b32 s12, v254, 22
	v_add_u32_e32 v21, 0xffffb3e0, v0
	v_readlane_b32 s13, v254, 23
	v_and_b32_e32 v0, 0xffffffc0, v21
	v_lshlrev_b32_e32 v21, 5, v21
	v_mov_b64_e32 v[22:23], s[12:13]
	s_mov_b32 s12, 0x2c00000
	v_and_b32_e32 v21, 0x7e0, v21
	v_mad_i64_i32 v[22:23], s[12:13], v36, s12, v[22:23]
	v_lshlrev_b64 v[24:25], 13, v[0:1]
	v_lshl_add_u64 v[22:23], v[22:23], 0, v[24:25]
	v_lshlrev_b32_e32 v24, 2, v21
	v_mov_b32_e32 v25, v1
	s_movk_i32 s12, 0x2c00
	v_lshl_add_u64 v[34:35], v[22:23], 0, v[24:25]
	v_mad_u64_u32 v[22:23], s[12:13], v21, s12, v[32:33]
	v_lshl_add_u64 v[22:23], v[0:1], 1, v[22:23]
	s_mov_b64 s[12:13], 0x4d00000
	v_lshl_add_u64 v[22:23], v[22:23], 0, s[12:13]

.LBB0_283:
	s_or_b64 exec, exec, s[8:9]
	v_mul_u32_u24_e32 v0, v21, v5
	v_lshlrev_b32_e32 v0, 2, v0
	v_lshl_add_u64 v[32:33], v[34:35], 0, v[0:1]
	v_lshlrev_b32_e32 v0, 2, v4
	v_lshl_add_u64 v[32:33], v[32:33], 0, v[0:1]
	v_lshlrev_b32_e32 v0, 1, v21
	v_lshl_add_u64 v[34:35], v[0:1], 2, v[32:33]
	v_lshlrev_b32_e32 v0, 2, v21
	v_lshl_add_u64 v[36:37], v[0:1], 2, v[32:33]
	v_mul_u32_u24_e32 v0, 6, v21
	v_lshlrev_b32_e32 v0, 2, v0
	v_lshl_add_u64 v[40:41], v[32:33], 0, v[0:1]
	v_lshlrev_b32_e32 v0, 3, v21
	v_lshl_add_u64 v[76:77], v[0:1], 2, v[32:33]
	v_mul_u32_u24_e32 v0, 10, v21
	v_lshlrev_b32_e32 v0, 2, v0
	v_lshl_add_u64 v[84:85], v[32:33], 0, v[0:1]
	v_mul_u32_u24_e32 v0, 12, v21
	v_lshlrev_b32_e32 v0, 2, v0
	v_lshl_add_u64 v[86:87], v[32:33], 0, v[0:1]
	v_mul_u32_u24_e32 v0, 14, v21
	v_lshlrev_b32_e32 v0, 2, v0
	v_lshl_add_u64 v[88:89], v[32:33], 0, v[0:1]
	v_lshlrev_b32_e32 v0, 4, v21
	s_mov_b32 s100, 1
	v_readfirstlane_b32 s0, v38
	v_readfirstlane_b32 s1, v39
	s_nop 3
	s_or_b32 s0, s0, s1
	s_cmp_eq_u32 s0, 0
	s_cbranch_scc1 .Lti_nogk_b
	v_mov_b32_e32 v136, v20
	v_mov_b32_e32 v137, 0
	v_lshl_add_u64 v[134:135], v[38:39], 0, v[136:137]
	global_load_dwordx4 v[130:133], v[134:135], off offset:16
	global_load_dwordx4 v[126:129], v[134:135], off
.Lti_nogk_b:
	global_load_dword v83, v[32:33], off
	global_load_dword v82, v[34:35], off
	global_load_dword v81, v[36:37], off
	global_load_dword v80, v[40:41], off
	global_load_dword v79, v[76:77], off
	global_load_dword v78, v[84:85], off
	s_nop 0
	global_load_dword v77, v[86:87], off
	global_load_dword v76, v[88:89], off
	v_lshl_add_u64 v[34:35], v[0:1], 2, v[32:33]
	v_mul_u32_u24_e32 v0, 18, v21
	v_lshlrev_b32_e32 v0, 2, v0
	v_lshl_add_u64 v[36:37], v[32:33], 0, v[0:1]
	v_mul_u32_u24_e32 v0, 20, v21
	v_lshlrev_b32_e32 v0, 2, v0
	v_lshl_add_u64 v[40:41], v[32:33], 0, v[0:1]
	v_mul_u32_u24_e32 v0, 22, v21
	v_lshlrev_b32_e32 v0, 2, v0
	v_lshl_add_u64 v[84:85], v[32:33], 0, v[0:1]
	v_mul_u32_u24_e32 v0, 24, v21
	v_lshlrev_b32_e32 v0, 2, v0
	v_lshl_add_u64 v[86:87], v[32:33], 0, v[0:1]
	v_mul_u32_u24_e32 v0, 26, v21
	v_lshlrev_b32_e32 v0, 2, v0
	v_lshl_add_u64 v[92:93], v[32:33], 0, v[0:1]
	v_mul_u32_u24_e32 v0, 28, v21
	v_lshlrev_b32_e32 v0, 2, v0
	v_lshl_add_u64 v[94:95], v[32:33], 0, v[0:1]
	v_mul_u32_u24_e32 v0, 30, v21
	v_lshlrev_b32_e32 v0, 2, v0
	v_lshl_add_u64 v[96:97], v[32:33], 0, v[0:1]
	v_lshlrev_b32_e32 v0, 5, v21
	global_load_dword v91, v[34:35], off
	global_load_dword v90, v[36:37], off
	global_load_dword v89, v[40:41], off
	global_load_dword v88, v[84:85], off
	s_nop 0
	global_load_dword v87, v[86:87], off
	s_nop 0
	global_load_dword v86, v[92:93], off
	global_load_dword v85, v[94:95], off
	global_load_dword v84, v[96:97], off
	v_lshl_add_u64 v[34:35], v[0:1], 2, v[32:33]
	v_mul_u32_u24_e32 v0, 34, v21
	v_lshlrev_b32_e32 v0, 2, v0
	v_lshl_add_u64 v[36:37], v[32:33], 0, v[0:1]
	v_mul_u32_u24_e32 v0, 36, v21
	v_lshlrev_b32_e32 v0, 2, v0
	v_lshl_add_u64 v[40:41], v[32:33], 0, v[0:1]
	v_mul_u32_u24_e32 v0, 38, v21
	v_lshlrev_b32_e32 v0, 2, v0
	v_lshl_add_u64 v[92:93], v[32:33], 0, v[0:1]
	v_mul_u32_u24_e32 v0, 40, v21
	v_lshlrev_b32_e32 v0, 2, v0
	v_lshl_add_u64 v[94:95], v[32:33], 0, v[0:1]
	v_mul_u32_u24_e32 v0, 42, v21
	v_lshlrev_b32_e32 v0, 2, v0
	v_lshl_add_u64 v[100:101], v[32:33], 0, v[0:1]
	v_mul_u32_u24_e32 v0, 44, v21
	v_lshlrev_b32_e32 v0, 2, v0
	v_lshl_add_u64 v[102:103], v[32:33], 0, v[0:1]
	v_mul_u32_u24_e32 v0, 46, v21
	v_lshlrev_b32_e32 v0, 2, v0
	v_lshl_add_u64 v[104:105], v[32:33], 0, v[0:1]
	v_mul_u32_u24_e32 v0, 48, v21
	v_lshlrev_b32_e32 v0, 2, v0
	global_load_dword v99, v[34:35], off
	global_load_dword v98, v[36:37], off
	global_load_dword v97, v[40:41], off
	global_load_dword v96, v[92:93], off
	s_nop 0
	global_load_dword v95, v[94:95], off
	s_nop 0
	global_load_dword v94, v[100:101], off
	global_load_dword v93, v[102:103], off
	global_load_dword v92, v[104:105], off
	v_lshl_add_u64 v[34:35], v[32:33], 0, v[0:1]
	v_mul_u32_u24_e32 v0, 50, v21
	v_lshlrev_b32_e32 v0, 2, v0
	v_lshl_add_u64 v[36:37], v[32:33], 0, v[0:1]
	v_mul_u32_u24_e32 v0, 52, v21
	v_lshlrev_b32_e32 v0, 2, v0
	v_lshl_add_u64 v[40:41], v[32:33], 0, v[0:1]
	v_mul_u32_u24_e32 v0, 54, v21
	v_lshlrev_b32_e32 v0, 2, v0
	v_lshl_add_u64 v[100:101], v[32:33], 0, v[0:1]
	v_mul_u32_u24_e32 v0, 56, v21
	v_lshlrev_b32_e32 v0, 2, v0
	v_lshl_add_u64 v[102:103], v[32:33], 0, v[0:1]
	v_mul_u32_u24_e32 v0, 58, v21
	v_lshlrev_b32_e32 v0, 2, v0
	v_lshl_add_u64 v[108:109], v[32:33], 0, v[0:1]
	v_mul_u32_u24_e32 v0, 60, v21
	v_lshlrev_b32_e32 v0, 2, v0
	v_lshl_add_u64 v[110:111], v[32:33], 0, v[0:1]
	v_mul_u32_u24_e32 v0, 62, v21
	v_lshlrev_b32_e32 v0, 2, v0
	v_lshl_add_u64 v[32:33], v[32:33], 0, v[0:1]
	global_load_dword v107, v[34:35], off
	global_load_dword v106, v[36:37], off
	global_load_dword v105, v[40:41], off
	global_load_dword v104, v[100:101], off
	s_nop 0
	global_load_dword v103, v[102:103], off
	s_nop 0
	global_load_dword v102, v[108:109], off
	global_load_dword v101, v[110:111], off
	global_load_dword v100, v[32:33], off
	v_cmp_ne_u64_e64 s[0:1], 0, v[38:39]
	s_and_saveexec_b64 s[8:9], s[0:1]
	s_xor_b64 s[0:1], exec, s[8:9]
	s_cbranch_execz .LBB0_285
	v_mov_b32_e32 v21, v1
	v_lshl_add_u64 v[32:33], v[38:39], 0, v[20:21]
	s_waitcnt vmcnt(32)
	v_pk_mul_f32 v[32:33], v[24:25], v[132:133] op_sel_hi:[0,1]
	v_pk_mul_f32 v[34:35], v[24:25], v[130:131] op_sel_hi:[0,1]
	v_pk_mul_f32 v[36:37], v[24:25], v[128:129] op_sel_hi:[0,1]
	v_pk_mul_f32 v[24:25], v[24:25], v[126:127] op_sel_hi:[0,1]

.LBB0_288:
	s_or_b64 exec, exec, s[6:7]
	v_add_u32_e32 v21, 0x400, v49
	v_add_u32_e32 v108, 0x800, v49
	v_add_u32_e32 v109, 0xc00, v49
	v_add_u32_e32 v110, 0x1000, v49
	v_add_u32_e32 v111, 0x1400, v49
	v_add_u32_e32 v112, 0x1800, v49
	v_add_u32_e32 v113, 0x1c00, v49
	s_waitcnt lgkmcnt(0)
	s_cmp_eq_u32 s100, 0
	s_cbranch_scc1 .Lti_w0_a
	s_waitcnt vmcnt(32)
	s_branch .Lti_wd_a

; __device__ __forceinline__ void phase_prologue(const Args& a, LAS unsigned char* lds) {
;     ...
;             if (it + 2 * NGW < I_ALL) { ta = titem_decode(a, it + 2 * NGW); TI_LOAD(ra, ga, ta); }
.Lti_wd_a:
	ds_write2_b32 v49, v11, v13 offset1:66
	ds_write2_b32 v49, v15, v42 offset0:132 offset1:198
	ds_write2_b32 v21, v43, v45 offset0:8 offset1:74
	ds_write2_b32 v21, v46, v47 offset0:140 offset1:206
	ds_write2_b32 v108, v51, v52 offset0:16 offset1:82
	ds_write2_b32 v108, v53, v54 offset0:148 offset1:214
	ds_write2_b32 v109, v55, v56 offset0:24 offset1:90
	ds_write2_b32 v109, v57, v58 offset0:156 offset1:222
	ds_write2_b32 v110, v59, v60 offset0:32 offset1:98
	ds_write2_b32 v110, v61, v62 offset0:164 offset1:230
	ds_write2_b32 v111, v63, v64 offset0:40 offset1:106
	ds_write2_b32 v111, v65, v66 offset0:172 offset1:238
	ds_write2_b32 v112, v68, v69 offset0:48 offset1:114
	ds_write2_b32 v112, v70, v71 offset0:180 offset1:246
	ds_write2_b32 v113, v72, v73 offset0:56 offset1:122
	ds_write2_b32 v113, v74, v75 offset0:188 offset1:254
	s_waitcnt lgkmcnt(0)
	ds_read2_b32 v[38:39], v44 offset1:33
	v_mad_i64_i32 v[120:121], s[0:1], v3, v18, 0
	v_add_u32_e32 v50, s70, v50
	s_mov_b32 s6, 0x1887f
	s_waitcnt lgkmcnt(0)
	v_mul_f32_e32 v0, v8, v38
	v_mul_f32_e32 v38, v9, v39
	v_cvt_pk_bf16_f32 v114, v0, v38
	ds_read2_b32 v[38:39], v44 offset0:66 offset1:99
	v_cmp_lt_i32_e64 s[38:39], s6, v50
	s_waitcnt lgkmcnt(0)
	v_mul_f32_e32 v0, v30, v38
	v_mul_f32_e32 v38, v31, v39
	v_cvt_pk_bf16_f32 v115, v0, v38
	ds_read2_b32 v[38:39], v44 offset0:132 offset1:165
	s_waitcnt lgkmcnt(0)
	v_mul_f32_e32 v0, v28, v38
	v_mul_f32_e32 v38, v29, v39
	v_cvt_pk_bf16_f32 v116, v0, v38
	ds_read2_b32 v[40:41], v44 offset0:198 offset1:231
	v_lshlrev_b32_e32 v38, 1, v12
	v_mov_b32_e32 v39, v1
	v_lshl_add_u64 v[118:119], v[6:7], 0, v[38:39]
	s_waitcnt lgkmcnt(0)
	v_mul_f32_e32 v0, v26, v40
	v_mul_f32_e32 v39, v27, v41
	v_mad_i64_i32 v[40:41], s[0:1], v3, v10, 0
	v_lshl_add_u64 v[40:41], v[40:41], 1, v[118:119]
	v_cvt_pk_bf16_f32 v117, v0, v39
	flat_store_dwordx4 v[40:41], v[114:117]
	ds_read2_b32 v[40:41], v44 offset0:8 offset1:41
	s_waitcnt lgkmcnt(0)
	v_mul_f32_e32 v0, v8, v40
	v_mul_f32_e32 v39, v9, v41
	v_cvt_pk_bf16_f32 v114, v0, v39
	ds_read2_b32 v[40:41], v44 offset0:74 offset1:107
	s_waitcnt lgkmcnt(0)
	v_mul_f32_e32 v0, v30, v40
	v_mul_f32_e32 v39, v31, v41
	v_cvt_pk_bf16_f32 v115, v0, v39
	ds_read2_b32 v[40:41], v44 offset0:140 offset1:173
	s_waitcnt lgkmcnt(0)
	v_mul_f32_e32 v0, v28, v40
	v_mul_f32_e32 v39, v29, v41
	v_cvt_pk_bf16_f32 v116, v0, v39
	ds_read2_b32 v[40:41], v44 offset0:206 offset1:239
	s_waitcnt lgkmcnt(0)
	v_mul_f32_e32 v0, v26, v40
	v_mul_f32_e32 v39, v27, v41
	v_mad_i64_i32 v[40:41], s[0:1], v3, v14, 0
	v_lshl_add_u64 v[40:41], v[40:41], 1, v[118:119]
	v_cvt_pk_bf16_f32 v117, v0, v39
	flat_store_dwordx4 v[40:41], v[114:117]
	ds_read2_b32 v[40:41], v44 offset0:16 offset1:49
	s_waitcnt lgkmcnt(0)
	v_mul_f32_e32 v0, v8, v40
	v_mul_f32_e32 v39, v9, v41
	v_cvt_pk_bf16_f32 v114, v0, v39
	ds_read2_b32 v[40:41], v44 offset0:82 offset1:115
	s_waitcnt lgkmcnt(0)
	v_mul_f32_e32 v0, v30, v40
	v_mul_f32_e32 v39, v31, v41
	v_cvt_pk_bf16_f32 v115, v0, v39
	ds_read2_b32 v[40:41], v44 offset0:148 offset1:181
	s_waitcnt lgkmcnt(0)
	v_mul_f32_e32 v0, v28, v40
	v_mul_f32_e32 v39, v29, v41
	v_cvt_pk_bf16_f32 v116, v0, v39
	ds_read2_b32 v[40:41], v44 offset0:214 offset1:247
	s_waitcnt lgkmcnt(0)
	v_mul_f32_e32 v0, v26, v40
	v_mul_f32_e32 v39, v27, v41
	v_mad_i64_i32 v[40:41], s[0:1], v3, v16, 0
	v_lshl_add_u64 v[40:41], v[40:41], 1, v[118:119]
	v_cvt_pk_bf16_f32 v117, v0, v39
	flat_store_dwordx4 v[40:41], v[114:117]
	ds_read2_b32 v[40:41], v44 offset0:24 offset1:57
	s_mov_b32 s0, 0x18880
	v_cmp_gt_i32_e64 s[0:1], s0, v50
	s_waitcnt lgkmcnt(0)
	v_mul_f32_e32 v0, v8, v40
	v_mul_f32_e32 v39, v9, v41
	v_cvt_pk_bf16_f32 v114, v0, v39
	ds_read2_b32 v[40:41], v44 offset0:90 offset1:123
	s_waitcnt lgkmcnt(0)
	v_mul_f32_e32 v0, v30, v40
	v_mul_f32_e32 v39, v31, v41
	v_cvt_pk_bf16_f32 v115, v0, v39
	ds_read2_b32 v[40:41], v44 offset0:156 offset1:189
	s_waitcnt lgkmcnt(0)
	v_mul_f32_e32 v0, v28, v40
	v_mul_f32_e32 v39, v29, v41
	v_cvt_pk_bf16_f32 v116, v0, v39
	ds_read2_b32 v[40:41], v44 offset0:222 offset1:255
	s_waitcnt lgkmcnt(0)
	v_mul_f32_e32 v0, v26, v40
	v_mul_f32_e32 v39, v27, v41
	v_lshl_add_u64 v[40:41], v[120:121], 1, v[118:119]
	v_cvt_pk_bf16_f32 v117, v0, v39
	flat_store_dwordx4 v[40:41], v[114:117]
	s_waitcnt lgkmcnt(0)
	s_and_saveexec_b64 s[6:7], s[0:1]
	s_cbranch_execz .LBB0_306
	s_mov_b32 s0, 0xa6f87fd7
	v_mul_hi_i32 v0, v50, s0
	v_add_u32_e32 v0, v0, v50
	v_lshrrev_b32_e32 v3, 31, v0
	v_ashrrev_i32_e32 v0, 14, v0
	v_add_u32_e32 v30, v0, v3
	v_mov_b64_e32 v[6:7], s[56:57]
	v_mul_i32_i24_e32 v8, 0x6220, v30
	v_mad_i64_i32 v[26:27], s[0:1], v30, s77, v[6:7]
	v_sub_u32_e32 v0, v50, v8
	s_movk_i32 s0, 0x181f
	v_ashrrev_i32_e32 v31, 31, v30
	v_cmp_lt_i32_e64 s[0:1], s0, v0
	s_and_saveexec_b64 s[8:9], s[0:1]
	s_xor_b64 s[8:9], exec, s[8:9]
	s_cbranch_execz .LBB0_299
	s_movk_i32 s0, 0x201f
	v_cmp_lt_u32_e64 s[0:1], s0, v0
	s_and_saveexec_b64 s[10:11], s[0:1]
	s_xor_b64 s[10:11], exec, s[10:11]
	s_cbranch_execz .LBB0_296
	s_movk_i32 s0, 0x4c1f
	v_cmp_lt_u32_e64 s[0:1], s0, v0
	s_and_saveexec_b64 s[12:13], s[0:1]
	s_xor_b64 s[0:1], exec, s[12:13]
	s_cbranch_execz .LBB0_293
	v_lshlrev_b32_e32 v3, 5, v8
	v_readlane_b32 s12, v254, 22
	v_add_u32_e32 v0, 0xffffb3e0, v0
	v_sub_u32_e32 v3, v48, v3
	v_readlane_b32 s13, v254, 23
	v_and_b32_e32 v0, 0xffffffc0, v0
	v_add_u32_e32 v3, 0xfff67c00, v3
	v_mov_b64_e32 v[6:7], s[12:13]
	s_mov_b32 s12, 0x2c00000
	v_and_b32_e32 v3, 0x7e0, v3
	v_mad_i64_i32 v[6:7], s[12:13], v30, s12, v[6:7]
	v_lshlrev_b64 v[8:9], 13, v[0:1]
	v_lshl_add_u64 v[6:7], v[6:7], 0, v[8:9]
	v_lshlrev_b32_e32 v8, 2, v3
	v_mov_b32_e32 v9, v1
	s_movk_i32 s12, 0x2c00
	v_lshl_add_u64 v[28:29], v[6:7], 0, v[8:9]
	v_mad_u64_u32 v[6:7], s[12:13], v3, s12, v[26:27]
	v_lshl_add_u64 v[6:7], v[0:1], 1, v[6:7]
	s_mov_b64 s[12:13], 0x4d00000
	v_lshl_add_u64 v[6:7], v[6:7], 0, s[12:13]

; __device__ __forceinline__ void phase_prologue(const Args& a, LAS unsigned char* lds) {
;     ...
;             if (it + 2 * NGW < I_ALL) { ta = titem_decode(a, it + 2 * NGW); TI_LOAD(ra, ga, ta); }
.LBB0_301:
	s_or_b64 exec, exec, s[8:9]
	v_mul_u32_u24_e32 v0, v9, v5
	v_lshlrev_b32_e32 v0, 2, v0
	v_lshl_add_u64 v[26:27], v[28:29], 0, v[0:1]
	v_lshlrev_b32_e32 v0, 2, v4
	v_lshl_add_u64 v[26:27], v[26:27], 0, v[0:1]
	v_lshlrev_b32_e32 v0, 1, v9
	v_lshl_add_u64 v[28:29], v[0:1], 2, v[26:27]
	v_lshlrev_b32_e32 v0, 2, v9
	v_lshl_add_u64 v[30:31], v[0:1], 2, v[26:27]
	v_mul_u32_u24_e32 v0, 6, v9
	v_lshlrev_b32_e32 v0, 2, v0
	v_lshl_add_u64 v[42:43], v[26:27], 0, v[0:1]
	v_lshlrev_b32_e32 v0, 3, v9
	v_lshl_add_u64 v[46:47], v[0:1], 2, v[26:27]
	v_mul_u32_u24_e32 v0, 10, v9
	v_lshlrev_b32_e32 v0, 2, v0
	v_lshl_add_u64 v[52:53], v[26:27], 0, v[0:1]
	v_mul_u32_u24_e32 v0, 12, v9
	v_lshlrev_b32_e32 v0, 2, v0
	v_lshl_add_u64 v[54:55], v[26:27], 0, v[0:1]
	v_mul_u32_u24_e32 v0, 14, v9
	v_lshlrev_b32_e32 v0, 2, v0
	v_lshl_add_u64 v[56:57], v[26:27], 0, v[0:1]
	v_lshlrev_b32_e32 v0, 4, v9
	s_mov_b32 s101, 1
	v_readfirstlane_b32 s0, v40
	v_readfirstlane_b32 s1, v41
	s_nop 3
	s_or_b32 s0, s0, s1
	s_cmp_eq_u32 s0, 0
	s_cbranch_scc1 .Lti_nogk_c
	v_lshlrev_b32_e32 v150, 2, v12
	v_mov_b32_e32 v151, 0
	v_lshl_add_u64 v[148:149], v[40:41], 0, v[150:151]
	global_load_dwordx4 v[144:147], v[148:149], off offset:16
	global_load_dwordx4 v[140:143], v[148:149], off
.Lti_nogk_c:
	global_load_dword v11, v[26:27], off
	global_load_dword v13, v[28:29], off
	global_load_dword v15, v[30:31], off
	s_nop 0
	global_load_dword v42, v[42:43], off
	s_nop 0
	global_load_dword v43, v[46:47], off
	global_load_dword v45, v[52:53], off
	s_nop 0
	global_load_dword v46, v[54:55], off
	global_load_dword v47, v[56:57], off
	v_lshl_add_u64 v[28:29], v[0:1], 2, v[26:27]
	v_mul_u32_u24_e32 v0, 18, v9
	v_lshlrev_b32_e32 v0, 2, v0
	v_lshl_add_u64 v[30:31], v[26:27], 0, v[0:1]
	v_mul_u32_u24_e32 v0, 20, v9
	v_lshlrev_b32_e32 v0, 2, v0
	v_lshl_add_u64 v[54:55], v[26:27], 0, v[0:1]
	v_mul_u32_u24_e32 v0, 22, v9
	v_lshlrev_b32_e32 v0, 2, v0
	v_lshl_add_u64 v[56:57], v[26:27], 0, v[0:1]
	v_mul_u32_u24_e32 v0, 24, v9
	v_lshlrev_b32_e32 v0, 2, v0
	v_lshl_add_u64 v[58:59], v[26:27], 0, v[0:1]
	v_mul_u32_u24_e32 v0, 26, v9
	v_lshlrev_b32_e32 v0, 2, v0
	v_lshl_add_u64 v[60:61], v[26:27], 0, v[0:1]
	v_mul_u32_u24_e32 v0, 28, v9
	v_lshlrev_b32_e32 v0, 2, v0
	v_lshl_add_u64 v[62:63], v[26:27], 0, v[0:1]
	v_mul_u32_u24_e32 v0, 30, v9
	v_lshlrev_b32_e32 v0, 2, v0
	v_lshl_add_u64 v[64:65], v[26:27], 0, v[0:1]
	v_lshlrev_b32_e32 v0, 5, v9
	global_load_dword v51, v[28:29], off
	global_load_dword v52, v[30:31], off
	global_load_dword v53, v[54:55], off
	s_nop 0
	global_load_dword v54, v[56:57], off
	global_load_dword v55, v[58:59], off
	s_nop 0
	global_load_dword v56, v[60:61], off
	global_load_dword v57, v[62:63], off
	global_load_dword v58, v[64:65], off
	v_lshl_add_u64 v[28:29], v[0:1], 2, v[26:27]
	v_mul_u32_u24_e32 v0, 34, v9
	v_lshlrev_b32_e32 v0, 2, v0
	v_lshl_add_u64 v[30:31], v[26:27], 0, v[0:1]
	v_mul_u32_u24_e32 v0, 36, v9
	v_lshlrev_b32_e32 v0, 2, v0
	v_lshl_add_u64 v[62:63], v[26:27], 0, v[0:1]
	v_mul_u32_u24_e32 v0, 38, v9
	v_lshlrev_b32_e32 v0, 2, v0
	v_lshl_add_u64 v[64:65], v[26:27], 0, v[0:1]
	v_mul_u32_u24_e32 v0, 40, v9
	v_lshlrev_b32_e32 v0, 2, v0
	v_lshl_add_u64 v[68:69], v[26:27], 0, v[0:1]
	v_mul_u32_u24_e32 v0, 42, v9
	v_lshlrev_b32_e32 v0, 2, v0
	v_lshl_add_u64 v[70:71], v[26:27], 0, v[0:1]
	v_mul_u32_u24_e32 v0, 44, v9
	v_lshlrev_b32_e32 v0, 2, v0
	v_lshl_add_u64 v[72:73], v[26:27], 0, v[0:1]
	v_mul_u32_u24_e32 v0, 46, v9
	v_lshlrev_b32_e32 v0, 2, v0
	v_lshl_add_u64 v[74:75], v[26:27], 0, v[0:1]
	v_mul_u32_u24_e32 v0, 48, v9
	v_lshlrev_b32_e32 v0, 2, v0
	global_load_dword v59, v[28:29], off
	global_load_dword v60, v[30:31], off
	global_load_dword v61, v[62:63], off
	s_nop 0
	global_load_dword v62, v[64:65], off
	global_load_dword v63, v[68:69], off
	s_nop 0
	global_load_dword v64, v[70:71], off
	global_load_dword v65, v[72:73], off
	global_load_dword v66, v[74:75], off
	v_lshl_add_u64 v[28:29], v[26:27], 0, v[0:1]
	v_mul_u32_u24_e32 v0, 50, v9
	v_lshlrev_b32_e32 v0, 2, v0
	v_lshl_add_u64 v[30:31], v[26:27], 0, v[0:1]
	v_mul_u32_u24_e32 v0, 52, v9
	v_lshlrev_b32_e32 v0, 2, v0
	v_lshl_add_u64 v[70:71], v[26:27], 0, v[0:1]
	v_mul_u32_u24_e32 v0, 54, v9
	v_lshlrev_b32_e32 v0, 2, v0
	v_lshl_add_u64 v[72:73], v[26:27], 0, v[0:1]
	v_mul_u32_u24_e32 v0, 56, v9
	v_lshlrev_b32_e32 v0, 2, v0
	v_lshl_add_u64 v[74:75], v[26:27], 0, v[0:1]
	v_mul_u32_u24_e32 v0, 58, v9
	v_lshlrev_b32_e32 v0, 2, v0
	v_lshl_add_u64 v[114:115], v[26:27], 0, v[0:1]
	v_mul_u32_u24_e32 v0, 60, v9
	v_lshlrev_b32_e32 v0, 2, v0
	v_lshl_add_u64 v[116:117], v[26:27], 0, v[0:1]
	v_mul_u32_u24_e32 v0, 62, v9
	v_lshlrev_b32_e32 v0, 2, v0
	v_lshl_add_u64 v[26:27], v[26:27], 0, v[0:1]
	global_load_dword v68, v[28:29], off
	global_load_dword v69, v[30:31], off
	s_nop 0
	global_load_dword v70, v[70:71], off
	s_nop 0
	global_load_dword v71, v[72:73], off
	s_nop 0
	global_load_dword v72, v[74:75], off
	global_load_dword v73, v[114:115], off
	s_nop 0
	global_load_dword v74, v[116:117], off
	global_load_dword v75, v[26:27], off
	v_cmp_ne_u64_e64 s[0:1], 0, v[40:41]
	s_and_saveexec_b64 s[8:9], s[0:1]
	s_xor_b64 s[0:1], exec, s[8:9]
	s_cbranch_execz .LBB0_303
	v_lshlrev_b32_e32 v0, 2, v12
	v_lshl_add_u64 v[26:27], v[40:41], 0, v[0:1]
	s_waitcnt vmcnt(32)
	v_pk_mul_f32 v[26:27], v[8:9], v[146:147] op_sel_hi:[0,1]
	v_pk_mul_f32 v[28:29], v[8:9], v[144:145] op_sel_hi:[0,1]
	v_pk_mul_f32 v[30:31], v[8:9], v[142:143] op_sel_hi:[0,1]
	v_pk_mul_f32 v[8:9], v[8:9], v[140:141] op_sel_hi:[0,1]

; __device__ __forceinline__ void phase_prologue(const Args& a, LAS unsigned char* lds) {
;     ...
;             if (hasB) TI_PROC(rb, gb, tb);
.LBB0_306:
	s_or_b64 exec, exec, s[6:7]
	s_waitcnt lgkmcnt(0)
	s_cmp_eq_u32 s101, 0
	s_cbranch_scc1 .Lti_w0_b2
	s_waitcnt vmcnt(32)
	s_branch .Lti_wd_b2

; __device__ __forceinline__ void phase_prologue(const Args& a, LAS unsigned char* lds) {
;     ...
;         for (int it = gw; it < I_ALL; it += 2 * NGW) {
;             const bool hasB = it + NGW < I_ALL;
;             if (hasB) { tb = titem_decode(a, it + NGW); TI_LOAD(rb, gb, tb); }
;             TI_PROC(ra, ga, ta);
;             if (it + 2 * NGW < I_ALL) { ta = titem_decode(a, it + 2 * NGW); TI_LOAD(ra, ga, ta); }
;             if (hasB) TI_PROC(rb, gb, tb);
.Lti_wd_b2:
	s_and_b64 s[0:1], exec, s[38:39]
	s_or_b64 s[4:5], s[0:1], s[4:5]
	s_and_saveexec_b64 s[0:1], vcc
	s_cbranch_execz .LBB0_269
	ds_write2_b32 v49, v83, v82 offset1:66
	ds_write2_b32 v49, v81, v80 offset0:132 offset1:198
	ds_write2_b32 v21, v79, v78 offset0:8 offset1:74
	ds_write2_b32 v21, v77, v76 offset0:140 offset1:206
	ds_write2_b32 v108, v91, v90 offset0:16 offset1:82
	ds_write2_b32 v108, v89, v88 offset0:148 offset1:214
	ds_write2_b32 v109, v87, v86 offset0:24 offset1:90
	ds_write2_b32 v109, v85, v84 offset0:156 offset1:222
	ds_write2_b32 v110, v99, v98 offset0:32 offset1:98
	ds_write2_b32 v110, v97, v96 offset0:164 offset1:230
	ds_write2_b32 v111, v95, v94 offset0:40 offset1:106
	ds_write2_b32 v111, v93, v92 offset0:172 offset1:238
	ds_write2_b32 v112, v107, v106 offset0:48 offset1:114
	ds_write2_b32 v112, v105, v104 offset0:180 offset1:246
	ds_write2_b32 v113, v103, v102 offset0:56 offset1:122
	ds_write2_b32 v113, v101, v100 offset0:188 offset1:254
	s_waitcnt lgkmcnt(0)
	ds_read2_b32 v[40:41], v44 offset1:33
	v_mov_b32_e32 v39, v1
	v_lshl_add_u64 v[112:113], v[22:23], 0, v[38:39]
	v_mad_i64_i32 v[38:39], s[6:7], v67, v10, 0
	s_waitcnt lgkmcnt(0)
	v_mul_f32_e32 v0, v24, v40
	v_mul_f32_e32 v21, v25, v41
	v_cvt_pk_bf16_f32 v108, v0, v21
	ds_read2_b32 v[40:41], v44 offset0:66 offset1:99
	v_lshl_add_u64 v[38:39], v[38:39], 1, v[112:113]
	s_waitcnt lgkmcnt(0)
	v_mul_f32_e32 v0, v36, v40
	v_mul_f32_e32 v21, v37, v41
	v_cvt_pk_bf16_f32 v109, v0, v21
	ds_read2_b32 v[40:41], v44 offset0:132 offset1:165
	s_waitcnt lgkmcnt(0)
	v_mul_f32_e32 v0, v34, v40
	v_mul_f32_e32 v21, v35, v41
	v_cvt_pk_bf16_f32 v110, v0, v21
	ds_read2_b32 v[40:41], v44 offset0:198 offset1:231
	s_waitcnt lgkmcnt(0)
	v_mul_f32_e32 v0, v32, v40
	v_mul_f32_e32 v21, v33, v41
	v_cvt_pk_bf16_f32 v111, v0, v21
	flat_store_dwordx4 v[38:39], v[108:111]
	ds_read2_b32 v[38:39], v44 offset0:8 offset1:41
	s_waitcnt lgkmcnt(0)
	v_mul_f32_e32 v0, v24, v38
	v_mul_f32_e32 v21, v25, v39
	v_cvt_pk_bf16_f32 v38, v0, v21
	ds_read2_b32 v[40:41], v44 offset0:74 offset1:107
	v_mad_i64_i32 v[110:111], s[6:7], v67, v16, 0
	v_lshl_add_u64 v[110:111], v[110:111], 1, v[112:113]
	s_waitcnt lgkmcnt(0)
	v_mul_f32_e32 v0, v36, v40
	v_mul_f32_e32 v21, v37, v41
	v_cvt_pk_bf16_f32 v39, v0, v21
	ds_read2_b32 v[40:41], v44 offset0:140 offset1:173
	s_waitcnt lgkmcnt(0)
	v_mul_f32_e32 v0, v34, v40
	v_mul_f32_e32 v21, v35, v41
	v_cvt_pk_bf16_f32 v40, v0, v21
	ds_read2_b32 v[108:109], v44 offset0:206 offset1:239
	s_waitcnt lgkmcnt(0)
	v_mul_f32_e32 v0, v32, v108
	v_mul_f32_e32 v21, v33, v109
	v_mad_i64_i32 v[108:109], s[6:7], v67, v14, 0
	v_lshl_add_u64 v[108:109], v[108:109], 1, v[112:113]
	v_cvt_pk_bf16_f32 v41, v0, v21
	flat_store_dwordx4 v[108:109], v[38:41]
	ds_read2_b32 v[38:39], v44 offset0:16 offset1:49
	s_waitcnt lgkmcnt(0)
	v_mul_f32_e32 v0, v24, v38
	v_mul_f32_e32 v21, v25, v39
	v_cvt_pk_bf16_f32 v38, v0, v21
	ds_read2_b32 v[40:41], v44 offset0:82 offset1:115
	s_waitcnt lgkmcnt(0)
	v_mul_f32_e32 v0, v36, v40
	v_mul_f32_e32 v21, v37, v41
	v_cvt_pk_bf16_f32 v39, v0, v21
	ds_read2_b32 v[40:41], v44 offset0:148 offset1:181
	s_waitcnt lgkmcnt(0)
	v_mul_f32_e32 v0, v34, v40
	v_mul_f32_e32 v21, v35, v41
	v_cvt_pk_bf16_f32 v40, v0, v21
	ds_read2_b32 v[108:109], v44 offset0:214 offset1:247
	s_waitcnt lgkmcnt(0)
	v_mul_f32_e32 v0, v32, v108
	v_mul_f32_e32 v21, v33, v109
	v_cvt_pk_bf16_f32 v41, v0, v21
	flat_store_dwordx4 v[110:111], v[38:41]
	ds_read2_b32 v[38:39], v44 offset0:24 offset1:57
	v_mad_i64_i32 v[110:111], s[6:7], v67, v18, 0
	s_waitcnt lgkmcnt(0)
	v_mul_f32_e32 v0, v24, v38
	v_mul_f32_e32 v21, v25, v39
	v_cvt_pk_bf16_f32 v38, v0, v21
	ds_read2_b32 v[40:41], v44 offset0:90 offset1:123
	s_waitcnt lgkmcnt(0)
	v_mul_f32_e32 v0, v36, v40
	v_mul_f32_e32 v21, v37, v41
	v_cvt_pk_bf16_f32 v39, v0, v21
	ds_read2_b32 v[40:41], v44 offset0:156 offset1:189
	s_waitcnt lgkmcnt(0)
	v_mul_f32_e32 v0, v34, v40
	v_mul_f32_e32 v21, v35, v41
	v_cvt_pk_bf16_f32 v40, v0, v21
	ds_read2_b32 v[108:109], v44 offset0:222 offset1:255
	s_waitcnt lgkmcnt(0)
	v_mul_f32_e32 v0, v32, v108
	v_mul_f32_e32 v21, v33, v109
	v_lshl_add_u64 v[108:109], v[110:111], 1, v[112:113]
	v_cvt_pk_bf16_f32 v41, v0, v21
	flat_store_dwordx4 v[108:109], v[38:41]
	s_waitcnt lgkmcnt(0)
	s_branch .LBB0_269

; __device__ __forceinline__ unsigned cvt_pk_bf16(float lo, float hi) { unsigned r; asm volatile("v_cvt_pk_bf16_f32 %0, %1, %2" : "=v"(r) : "v"(lo), "v"(hi)); return r; }
; __device__ __forceinline__ void phase_prologue(const Args& a, LAS unsigned char* lds) {
;     ...
;         for (int m = gw; m < M; m += NGW) { const f32x4* xr = (const f32x4*)(a.x + (size_t)m * D) + lane; f32x4* orow = (f32x4*)(a.out + (size_t)m * D) + lane; u32x2* brow = (u32x2*)(xb + (size_t)m * D) + lane; float s = 0.f;
; #pragma unroll
;             for (int j = 0; j < 8; ++j) { const f32x4 v = xr[64 * j]; orow[64 * j] = v; s += (v[0] * v[0] + v[1] * v[1]) + (v[2] * v[2] + v[3] * v[3]);
;                 u32x2 w; w.x = cvt_pk_bf16(v[0], v[1]); w.y = cvt_pk_bf16(v[2], v[3]); brow[64 * j] = w; }
;             s = wave_sum(s); if (lane == 0) ss0[m] = (u64_t)(s * SS_FX + 0.5f); } }
.LBB0_314:
	v_lshl_add_u64 v[34:35], v[14:15], 0, v[0:1]
	flat_load_dwordx4 v[18:21], v[34:35]
	v_lshl_add_u64 v[22:23], s[98:99], 0, v[12:13]
	s_mov_b32 s0, 0x18f00000
	v_add_co_u32_e64 v50, s[0:1], s0, v22
	v_lshl_add_u64 v[38:39], v[10:11], 0, v[0:1]
	s_nop 0
	v_addc_co_u32_e64 v51, s[0:1], 0, v23, s[0:1]
	v_add_co_u32_e64 v46, s[0:1], s94, v34
	v_and_b32_e32 v3, 64, v208
	s_nop 0
	v_addc_co_u32_e64 v47, s[0:1], 0, v35, s[0:1]
	v_add_co_u32_e64 v52, s[0:1], s94, v38
	s_waitcnt lgkmcnt(0)
	v_xor_b32_e32 v5, 1, v208
	v_addc_co_u32_e64 v53, s[0:1], 0, v39, s[0:1]
	v_add_u32_e32 v3, 64, v3
	v_cmp_lt_i32_e64 s[0:1], v5, v3
	flat_load_dwordx4 v[100:103], v[34:35] offset:1024
	flat_load_dwordx4 v[104:107], v[34:35] offset:2048
	flat_load_dwordx4 v[108:111], v[34:35] offset:3072
	flat_load_dwordx4 v[112:115], v[46:47]
	flat_load_dwordx4 v[116:119], v[46:47] offset:1024
	flat_load_dwordx4 v[120:123], v[46:47] offset:2048
	flat_load_dwordx4 v[124:127], v[46:47] offset:3072
	s_waitcnt vmcnt(0) lgkmcnt(0)
	flat_store_dwordx4 v[38:39], v[18:21]
	v_cvt_pk_bf16_f32 v22, v18, v19
	v_cvt_pk_bf16_f32 v23, v20, v21
	flat_store_dwordx2 v[50:51], v[22:23]
	s_nop 1
	v_mov_b32_e32 v22, v100
	v_mov_b32_e32 v23, v101
	v_mov_b32_e32 v24, v102
	v_mov_b32_e32 v25, v103
	v_mul_f32_e32 v7, v19, v19
	v_mul_f32_e32 v16, v21, v21
	v_fmac_f32_e32 v7, v18, v18
	v_fmac_f32_e32 v16, v20, v20
	v_add_f32_e32 v7, v7, v16
	v_cndmask_b32_e64 v5, v208, v5, s[0:1]
	v_lshlrev_b32_e32 v5, 2, v5
	s_waitcnt lgkmcnt(0)
	flat_store_dwordx4 v[38:39], v[22:25] offset:1024
	v_cvt_pk_bf16_f32 v26, v22, v23
	v_cvt_pk_bf16_f32 v27, v24, v25
	flat_store_dwordx2 v[50:51], v[26:27] offset:512
	s_nop 1
	v_mov_b32_e32 v26, v104
	v_mov_b32_e32 v27, v105
	v_mov_b32_e32 v28, v106
	v_mov_b32_e32 v29, v107
	v_mul_f32_e32 v16, v23, v23
	v_mul_f32_e32 v18, v25, v25
	v_fmac_f32_e32 v16, v22, v22
	v_fmac_f32_e32 v18, v24, v24
	v_add_f32_e32 v16, v16, v18
	v_add_f32_e32 v7, v7, v16
	s_waitcnt lgkmcnt(0)
	flat_store_dwordx4 v[38:39], v[26:29] offset:2048
	v_cvt_pk_bf16_f32 v30, v26, v27
	v_cvt_pk_bf16_f32 v31, v28, v29
	flat_store_dwordx2 v[50:51], v[30:31] offset:1024
	s_nop 1
	v_mov_b32_e32 v30, v108
	v_mov_b32_e32 v31, v109
	v_mov_b32_e32 v32, v110
	v_mov_b32_e32 v33, v111
	v_mul_f32_e32 v16, v27, v27
	v_mul_f32_e32 v18, v29, v29
	v_fmac_f32_e32 v16, v26, v26
	v_fmac_f32_e32 v18, v28, v28
	v_add_f32_e32 v16, v16, v18
	v_add_f32_e32 v7, v7, v16
	s_waitcnt lgkmcnt(0)
	flat_store_dwordx4 v[38:39], v[30:33] offset:3072
	v_cvt_pk_bf16_f32 v34, v30, v31
	v_cvt_pk_bf16_f32 v35, v32, v33
	flat_store_dwordx2 v[50:51], v[34:35] offset:1536
	s_nop 1
	v_mov_b32_e32 v34, v112
	v_mov_b32_e32 v35, v113
	v_mov_b32_e32 v36, v114
	v_mov_b32_e32 v37, v115
	v_mul_f32_e32 v16, v31, v31
	v_mul_f32_e32 v18, v33, v33
	v_fmac_f32_e32 v16, v30, v30
	v_fmac_f32_e32 v18, v32, v32
	v_add_f32_e32 v16, v16, v18
	v_add_f32_e32 v7, v7, v16
	s_waitcnt lgkmcnt(0)
	flat_store_dwordx4 v[52:53], v[34:37]
	v_cvt_pk_bf16_f32 v38, v34, v35
	v_cvt_pk_bf16_f32 v39, v36, v37
	flat_store_dwordx2 v[50:51], v[38:39] offset:2048
	s_nop 1
	v_mov_b32_e32 v38, v116
	v_mov_b32_e32 v39, v117
	v_mov_b32_e32 v40, v118
	v_mov_b32_e32 v41, v119
	v_mul_f32_e32 v16, v35, v35
	v_mul_f32_e32 v18, v37, v37
	v_fmac_f32_e32 v16, v34, v34
	v_fmac_f32_e32 v18, v36, v36
	v_add_f32_e32 v16, v16, v18
	v_add_f32_e32 v7, v7, v16
	s_waitcnt lgkmcnt(0)
	flat_store_dwordx4 v[52:53], v[38:41] offset:1024
	v_cvt_pk_bf16_f32 v42, v38, v39
	v_cvt_pk_bf16_f32 v43, v40, v41
	flat_store_dwordx2 v[50:51], v[42:43] offset:2560
	s_nop 1
	v_mov_b32_e32 v42, v120
	v_mov_b32_e32 v43, v121
	v_mov_b32_e32 v44, v122
	v_mov_b32_e32 v45, v123
	v_mul_f32_e32 v16, v39, v39
	v_mul_f32_e32 v18, v41, v41
	v_fmac_f32_e32 v16, v38, v38
	v_fmac_f32_e32 v18, v40, v40
	v_add_f32_e32 v16, v16, v18
	v_add_f32_e32 v7, v7, v16
	s_waitcnt lgkmcnt(0)
	flat_store_dwordx4 v[52:53], v[42:45] offset:2048
	v_cvt_pk_bf16_f32 v48, v42, v43
	v_cvt_pk_bf16_f32 v49, v44, v45
	flat_store_dwordx2 v[50:51], v[48:49] offset:3072
	s_nop 1
	v_mov_b32_e32 v46, v124
	v_mov_b32_e32 v47, v125
	v_mov_b32_e32 v48, v126
	v_mov_b32_e32 v49, v127
	v_mul_f32_e32 v16, v43, v43
	v_mul_f32_e32 v18, v45, v45
	v_fmac_f32_e32 v16, v42, v42
	v_fmac_f32_e32 v18, v44, v44
	v_add_f32_e32 v16, v16, v18
	v_add_f32_e32 v7, v7, v16
	s_waitcnt lgkmcnt(0)
	v_mul_f32_e32 v16, v47, v47
	v_mul_f32_e32 v18, v49, v49
	v_fmac_f32_e32 v16, v46, v46
	v_fmac_f32_e32 v18, v48, v48
	v_add_f32_e32 v16, v16, v18
	v_add_f32_e32 v7, v7, v16
	ds_bpermute_b32 v5, v5, v7
	v_xor_b32_e32 v16, 2, v208
	v_cmp_lt_i32_e64 s[0:1], v16, v3
	flat_store_dwordx4 v[52:53], v[46:49] offset:3072
	v_cvt_pk_bf16_f32 v18, v46, v47
	s_waitcnt lgkmcnt(0)
	v_add_f32_e32 v5, v7, v5
	v_cndmask_b32_e64 v16, v208, v16, s[0:1]
	v_lshlrev_b32_e32 v16, 2, v16
	ds_bpermute_b32 v7, v16, v5
	v_xor_b32_e32 v16, 4, v208
	v_cmp_lt_i32_e64 s[0:1], v16, v3
	v_cvt_pk_bf16_f32 v19, v48, v49
	flat_store_dwordx2 v[50:51], v[18:19] offset:3584
	s_waitcnt lgkmcnt(0)
	v_add_f32_e32 v5, v5, v7
	v_cndmask_b32_e64 v16, v208, v16, s[0:1]
	v_lshlrev_b32_e32 v16, 2, v16
	ds_bpermute_b32 v7, v16, v5
	v_xor_b32_e32 v16, 8, v208
	v_cmp_lt_i32_e64 s[0:1], v16, v3
	s_waitcnt lgkmcnt(0)
	v_add_f32_e32 v5, v5, v7
	v_cndmask_b32_e64 v16, v208, v16, s[0:1]
	v_lshlrev_b32_e32 v16, 2, v16
	ds_bpermute_b32 v7, v16, v5
	v_xor_b32_e32 v16, 16, v208
	v_cmp_lt_i32_e64 s[0:1], v16, v3
	s_waitcnt lgkmcnt(0)
	v_add_f32_e32 v5, v5, v7
	v_cndmask_b32_e64 v16, v208, v16, s[0:1]
	v_lshlrev_b32_e32 v16, 2, v16
	ds_bpermute_b32 v7, v16, v5
	v_xor_b32_e32 v16, 32, v208
	v_cmp_lt_i32_e64 s[0:1], v16, v3
	s_waitcnt lgkmcnt(0)
	v_add_f32_e32 v3, v5, v7
	v_cndmask_b32_e64 v16, v208, v16, s[0:1]
	v_lshlrev_b32_e32 v5, 2, v16
	ds_bpermute_b32 v5, v5, v3
	s_and_saveexec_b64 s[0:1], vcc
	s_cbranch_execz .LBB0_313
	s_waitcnt lgkmcnt(0)
	v_add_f32_e32 v3, v3, v5
	s_mov_b32 s6, 0x4b800000
	v_fma_f32 v3, v3, s6, 0.5
	v_trunc_f32_e32 v3, v3
	v_mul_f32_e32 v5, 0x2f800000, v3
	v_floor_f32_e32 v5, v5
	v_fmac_f32_e32 v3, 0xcf800000, v5
	v_cvt_u32_f32_e32 v18, v3
	v_cvt_u32_f32_e32 v19, v5
	v_lshl_add_u64 v[20:21], s[98:99], 0, v[8:9]
	flat_store_dwordx2 v[20:21], v[18:19]
	s_branch .LBB0_313
